# panel barrier census fetched during P4's scan-done wait (cached), so SEAM(5)'s panel barrier has no census round trip
# baseline (speedup 1.0000x reference)
; __device__ __forceinline__ void grp_wait(unsigned* c, unsigned target) {
;     if (threadIdx.x == 0) {
;         unsigned sp = 0;
;         while (__hip_atomic_load(c, __ATOMIC_RELAXED, __HIP_MEMORY_SCOPE_AGENT) < target) { __builtin_amdgcn_s_sleep(2); if (++sp > (1u << 22)) break; }
;         __builtin_amdgcn_fence(__ATOMIC_ACQUIRE, "agent");
;         asm volatile("s_waitcnt vmcnt(0)" ::: "memory");
;     }
;     __syncthreads();
; }
; __global__ void __launch_bounds__(512, 2) mk_fwd(Args args) {
;     ...
;         if (scan_in_p2) grp_wait(cntS + 64 * (vb >> 5), 32u);
.LBB0_425:
	s_and_b32 s1, s2, 63
	s_lshl_b32 s1, s1, 8
	s_add_u32 s1, s1, 0xc000
	v_mov_b32_e32 v0, s1
	global_load_dword v1, v0, s[66:67] sc1
	buffer_inv sc1
	s_waitcnt vmcnt(0)
	s_getreg_b32 s1, hwreg(HW_REG_XCC_ID, 0, 4)
	s_and_b32 s1, s1, 7
	s_mul_i32 s1, s1, 3
	v_readfirstlane_b32 s6, v1
	s_lshr_b32 s6, s6, s1
	s_and_b32 s6, s6, 7
	v_writelane_b32 v251, s6, 9

; __device__ __forceinline__ unsigned xb_ld(unsigned* p)              { return __hip_atomic_load(p, __ATOMIC_RELAXED, __HIP_MEMORY_SCOPE_AGENT); }
; __device__ __forceinline__ unsigned xb_add(unsigned* p, unsigned v) { return __hip_atomic_fetch_add(p, v, __ATOMIC_RELAXED, __HIP_MEMORY_SCOPE_AGENT); }
; #define XB_SPIN(cond, bar) do { unsigned _sp = 0; while (cond) { __builtin_amdgcn_s_sleep(1); \
;     if ((++_sp & 255u) == 0u) { if (xb_ld(&(bar)[XB_TMO])) break; if (_sp > XB_SPIN_CAP) { atomicAdd(&(bar)[XB_TMO], 1u); break; } } } } while (0)
; #define SEAM(k) do { if (IN(k) && IN((k) + 1)) xcd_barrier(bar); } while (0)
; __device__ __forceinline__ void xcd_barrier(const XcdBarrier& b) {
;     asm volatile("s_waitcnt vmcnt(0)" ::: "memory");
;     __syncthreads();
;     if (threadIdx.x == 0) {
;         unsigned* bar = b.bar;
;         __builtin_amdgcn_s_waitcnt(0);
;         unsigned nloc = b.st[0], nx = b.st[1];
;         if (nloc == 0u) { xcd_barrier_complete(bar, b.x, nloc, nx); b.st[0] = nloc; b.st[1] = nx; }
;         const unsigned old = xb_add(&bar[XB_XSUB(b.x)], 1u);
;         const unsigned gen = old / nloc;
;         if (old + 1u == (gen + 1u) * nloc) {
;             __builtin_amdgcn_fence(__ATOMIC_RELEASE, "agent");
;             asm volatile("s_waitcnt vmcnt(0)" ::: "memory");
;             const unsigned og = xb_add(&bar[XB_TOP], 1u);
;             const unsigned tg = og / nx;
;             if (og + 1u == (tg + 1u) * nx) xb_add(&bar[XB_TOPGEN], 1u);
;             else XB_SPIN(xb_ld(&bar[XB_TOPGEN]) == tg, bar);
;             __builtin_amdgcn_fence(__ATOMIC_ACQUIRE, "agent");
;             xb_add(&bar[XB_XGEN(b.x)], 1u);
;             asm volatile("s_waitcnt vmcnt(0)" ::: "memory");
;         } else {
;             XB_SPIN(xb_ld(&bar[XB_XGEN(b.x)]) == gen, bar);
;             __builtin_amdgcn_fence(__ATOMIC_ACQUIRE, "agent");
;             asm volatile("s_waitcnt vmcnt(0)" ::: "memory");
;         }
;     }
;     __syncthreads();
; }
; __global__ void __launch_bounds__(512, 2) mk_fwd(Args args) {
;     ...
;     SEAM(5);
.LBB0_535:
	s_cmp_gt_i32 s69, 6
	s_cselect_b64 s[4:5], -1, 0
	s_and_b64 s[0:1], s[6:7], s[4:5]
	s_andn2_b64 vcc, exec, s[0:1]
	s_cbranch_vccnz .LBB0_589
	s_waitcnt vmcnt(0)
	s_waitcnt vmcnt(0)
	s_barrier
	s_and_saveexec_b64 s[6:7], s[92:93]
	s_cbranch_execz .LBB0_588
	s_and_b32 s0, s2, 63
	v_mov_b32_e32 v1, 1
	s_lshl_b32 s0, s0, 7
	s_add_u32 s0, s0, 0x8000
	v_mov_b32_e32 v0, s0
	v_readlane_b32 s1, v251, 9
	s_nop 0
	s_cmp_eq_u32 s1, 4
	s_cbranch_scc1 .Lpb5_fast
	buffer_wbl2 sc1
	s_waitcnt vmcnt(0)
